# barrier release spin loops poll back to back (s_sleep removed)
# speedup vs baseline: 1.0035x; 1.0035x over previous
; __device__ __forceinline__ unsigned xb_ld(unsigned* p)              { return __hip_atomic_load(p, __ATOMIC_RELAXED, __HIP_MEMORY_SCOPE_AGENT); }
; __device__ __forceinline__ unsigned xb_add(unsigned* p, unsigned v) { return __hip_atomic_fetch_add(p, v, __ATOMIC_RELAXED, __HIP_MEMORY_SCOPE_AGENT); }
; #define XB_SPIN(cond, bar) do { unsigned _sp = 0; while (cond) { __builtin_amdgcn_s_sleep(1); \
;     if ((++_sp & 255u) == 0u) { if (xb_ld(&(bar)[XB_TMO])) break; if (_sp > XB_SPIN_CAP) { atomicAdd(&(bar)[XB_TMO], 1u); break; } } } } while (0)
; __device__ __forceinline__ void xcd_barrier(const XcdBarrier& b) {
;     ...
;             const unsigned tg = og / nx;
;             if (og + 1u == (tg + 1u) * nx) xb_add(&bar[XB_TOPGEN], 1u);
;             else XB_SPIN(xb_ld(&bar[XB_TOPGEN]) == tg, bar);
;             __builtin_amdgcn_fence(__ATOMIC_ACQUIRE, "agent");
;             xb_add(&bar[XB_XGEN(b.x)], 1u);
;             asm volatile("s_waitcnt vmcnt(0)" ::: "memory");
;         } else {
;             XB_SPIN(xb_ld(&bar[XB_XGEN(b.x)]) == gen, bar);
;             __builtin_amdgcn_fence(__ATOMIC_ACQUIRE, "agent");
.LBB0_780:
	s_and_b32 s20, s24, 0xff
	s_mov_b64 s[18:19], -1
	s_cmp_lg_u32 s20, 0
	s_mov_b64 s[22:23], -1
	s_cbranch_scc1 .LBB0_783
	global_load_dword v0, v165, s[90:91] offset:512 sc1
	s_waitcnt vmcnt(0)
	v_cmp_eq_u32_e32 vcc, 0, v0
	s_cbranch_vccnz .LBB0_785
	s_mov_b64 s[22:23], 0
	s_mov_b64 s[20:21], -1

; __device__ __forceinline__ unsigned xb_ld(unsigned* p)              { return __hip_atomic_load(p, __ATOMIC_RELAXED, __HIP_MEMORY_SCOPE_AGENT); }
; __device__ __forceinline__ unsigned xb_add(unsigned* p, unsigned v) { return __hip_atomic_fetch_add(p, v, __ATOMIC_RELAXED, __HIP_MEMORY_SCOPE_AGENT); }
; #define XB_SPIN(cond, bar) do { unsigned _sp = 0; while (cond) { __builtin_amdgcn_s_sleep(1); \
;     if ((++_sp & 255u) == 0u) { if (xb_ld(&(bar)[XB_TMO])) break; if (_sp > XB_SPIN_CAP) { atomicAdd(&(bar)[XB_TMO], 1u); break; } } } } while (0)
; __device__ __forceinline__ void xcd_barrier(const XcdBarrier& b) {
;     ...
;             const unsigned tg = og / nx;
;             if (og + 1u == (tg + 1u) * nx) xb_add(&bar[XB_TOPGEN], 1u);
;             else XB_SPIN(xb_ld(&bar[XB_TOPGEN]) == tg, bar);
;             __builtin_amdgcn_fence(__ATOMIC_ACQUIRE, "agent");
;             xb_add(&bar[XB_XGEN(b.x)], 1u);
;             asm volatile("s_waitcnt vmcnt(0)" ::: "memory");
;         } else {
;             XB_SPIN(xb_ld(&bar[XB_XGEN(b.x)]) == gen, bar);
;             __builtin_amdgcn_fence(__ATOMIC_ACQUIRE, "agent");
.LBB0_797:
	s_and_b32 s22, s27, 0xff
	s_mov_b64 s[20:21], -1
	s_cmp_lg_u32 s22, 0
	s_mov_b64 s[24:25], -1
	s_cbranch_scc1 .LBB0_800
	global_load_dword v0, v165, s[12:13] sc1
	s_waitcnt vmcnt(0)
	v_cmp_eq_u32_e32 vcc, 0, v0
	s_cbranch_vccnz .LBB0_802
	s_mov_b64 s[24:25], 0
	s_mov_b64 s[22:23], -1
